# RSTAB per-tile loads batched: 12 loads issued together, single vmcnt wait
# baseline (speedup 1.0000x reference)
.LBB0_264:
	s_and_saveexec_b64 s[0:1], s[20:21]
	s_cbranch_execz .LBB0_267
	v_lshl_add_u32 v2, s23, 8, v0
	v_ashrrev_i32_e32 v3, 31, v2
	v_lshlrev_b64 v[2:3], 7, v[2:3]
	v_lshl_add_u64 v[18:19], s[70:71], 0, v[2:3]
	global_load_dwordx4 v[24:27], v[18:19], off
	global_load_dwordx4 v[28:31], v[18:19], off offset:16
	global_load_dwordx4 v[32:35], v[18:19], off offset:32
	global_load_dwordx4 v[36:39], v[18:19], off offset:48
	global_load_dwordx4 v[40:43], v[18:19], off offset:64
	global_load_dwordx4 v[44:47], v[18:19], off offset:80
	global_load_dwordx4 v[48:51], v[18:19], off offset:96
	global_load_dwordx4 v[52:55], v[18:19], off offset:112
	s_and_b32 s16, s48, 1
	s_lshl_b32 s17, s16, 10
	s_add_i32 s17, s17, 0
	v_lshl_add_u32 v56, v0, 2, s17
	v_add_u32_e32 v56, 0x20000, v56
	s_andn2_b64 vcc, exec, s[12:13]
	s_cbranch_vccnz .Lrs_reduce
	v_and_b32_e32 v2, 0x7f, v0
	v_lshl_or_b32 v2, s26, 7, v2
	v_lshrrev_b32_e32 v3, 7, v0
	s_movk_i32 s17, 0x1600
	s_lshl_b32 s16, s16, 12
	v_mad_u64_u32 v[2:3], s[20:21], v3, s17, v[2:3]
	s_add_i32 s16, s16, 0
	v_lshl_add_u32 v0, v0, 2, s16
	v_ashrrev_i32_e32 v3, 31, v2
	v_readlane_b32 s16, v236, 27
	v_lshlrev_b64 v[2:3], 2, v[2:3]
	v_readlane_b32 s17, v236, 28
	v_add_u32_e32 v0, 0x22800, v0
	s_nop 0
	v_lshl_add_u64 v[4:5], s[16:17], 0, v[2:3]
	v_add_co_u32_e32 v6, vcc, 0xb000, v4
	v_readlane_b32 s16, v236, 29
	s_nop 0
	v_addc_co_u32_e32 v7, vcc, 0, v5, vcc
	global_load_dword v8, v[4:5], off
	v_readlane_b32 s17, v236, 30
	global_load_dword v6, v[6:7], off
	v_add_co_u32_e32 v4, vcc, 0x16000, v4
	v_lshl_add_u64 v[2:3], s[16:17], 0, v[2:3]
	s_nop 0
	v_addc_co_u32_e32 v5, vcc, 0, v5, vcc
	global_load_dword v4, v[4:5], off
	global_load_dword v2, v[2:3], off
.Lrs_reduce:
	s_waitcnt vmcnt(0)
	v_pk_add_f32 v[26:27], v[26:27], v[30:31]
	v_pk_add_f32 v[24:25], v[24:25], v[28:29]
	v_pk_add_f32 v[26:27], v[26:27], v[34:35]
	v_pk_add_f32 v[24:25], v[24:25], v[32:33]
	v_pk_add_f32 v[26:27], v[26:27], v[38:39]
	v_pk_add_f32 v[24:25], v[24:25], v[36:37]
	v_pk_add_f32 v[26:27], v[26:27], v[42:43]
	v_pk_add_f32 v[24:25], v[24:25], v[40:41]
	v_pk_add_f32 v[26:27], v[26:27], v[46:47]
	v_pk_add_f32 v[24:25], v[24:25], v[44:45]
	v_pk_add_f32 v[26:27], v[26:27], v[50:51]
	v_pk_add_f32 v[24:25], v[24:25], v[48:49]
	v_pk_add_f32 v[26:27], v[26:27], v[54:55]
	v_pk_add_f32 v[24:25], v[24:25], v[52:53]
	s_nop 0
	v_pk_mov_b32 v[28:29], v[24:25], v[26:27] op_sel:[1,0]
	v_mov_b32_e32 v25, v27
	v_pk_add_f32 v[24:25], v[28:29], v[24:25]
	s_nop 0
	v_add_f32_e32 v24, v24, v25
	v_fmamk_f32 v24, v24, 0x3a000000, v207
	v_rsq_f32_e32 v24, v24
	s_nop 1
	ds_write_b32 v56, v24
	s_andn2_b64 vcc, exec, s[12:13]
	s_cbranch_vccnz .LBB0_267
	ds_write2st64_b32 v0, v8, v6 offset1:4
	ds_write2st64_b32 v0, v4, v2 offset0:8 offset1:12
